# grid barrier: non-leader workgroups poll the global generation word directly (expected value = static barrier index) instead of waiting one more hop for their XCD leader to republish it; leader's per-
# speedup vs baseline: 1.0067x; 1.0067x over previous
; DI int fresh_tid(int wid_s) { int l; asm volatile("v_mbcnt_lo_u32_b32 %0, -1, 0\n\tv_mbcnt_hi_u32_b32 %0, -1, %0" : "=v"(l)); return wid_s * 64 + l; }
; DI unsigned xb_ld(unsigned* p)              { return __hip_atomic_load(p, __ATOMIC_RELAXED, __HIP_MEMORY_SCOPE_AGENT); }
; DI unsigned xb_add(unsigned* p, unsigned v) { return __hip_atomic_fetch_add(p, v, __ATOMIC_RELAXED, __HIP_MEMORY_SCOPE_AGENT); }
; #define XB_SPIN(cond, bar) do { unsigned _sp = 0; while (cond) { __builtin_amdgcn_s_sleep(1); \
;     if ((++_sp & 255u) == 0u) { if (xb_ld(&(bar)[XB_TMO])) break; if (_sp > XB_SPIN_CAP) { atomicAdd(&(bar)[XB_TMO], 1u); break; } } } } while (0)
; DI void xcd_barrier(const XcdBarrier& b, const int wid_s) {
;     ...
;     if (fresh_tid(wid_s) == 0) {
;         unsigned* bar = b.bar;
;         __builtin_amdgcn_s_waitcnt(0);
;         unsigned nloc = b.st[0], nx = b.st[1];
;         if (nloc == 0u) { xcd_barrier_complete(bar, b.x, nloc, nx); b.st[0] = nloc; b.st[1] = nx; }
;         const unsigned old = xb_add(&bar[XB_XSUB(b.x)], 1u);
;         const unsigned gen = old / nloc;
;         if (old + 1u == (gen + 1u) * nloc) {
;             __builtin_amdgcn_fence(__ATOMIC_RELEASE, "agent");
;             asm volatile("s_waitcnt vmcnt(0)" ::: "memory");
;             const unsigned og = xb_add(&bar[XB_TOP], 1u);
;             const unsigned tg = og / nx;
;             if (og + 1u == (tg + 1u) * nx) xb_add(&bar[XB_TOPGEN], 1u);
;             else XB_SPIN(xb_ld(&bar[XB_TOPGEN]) == tg, bar);
;             __builtin_amdgcn_fence(__ATOMIC_ACQUIRE, "agent");
;             xb_add(&bar[XB_XGEN(b.x)], 1u);
;             asm volatile("s_waitcnt vmcnt(0)" ::: "memory");
;         } else {
;             XB_SPIN(xb_ld(&bar[XB_XGEN(b.x)]) == gen, bar);
.LBB0_58:
	s_or_b64 exec, exec, s[6:7]
	v_cvt_f32_u32_e32 v4, v2
	s_waitcnt vmcnt(0)
	v_readfirstlane_b32 s4, v3
	v_sub_u32_e32 v3, 0, v2
	v_rcp_iflag_f32_e32 v4, v4
	v_add_u32_e32 v5, s4, v1
	v_mul_f32_e32 v4, 0x4f7ffffe, v4
	v_cvt_u32_f32_e32 v4, v4
	v_mul_lo_u32 v1, v3, v4
	v_mul_hi_u32 v1, v4, v1
	v_add_u32_e32 v1, v4, v1
	v_mul_hi_u32 v1, v5, v1
	v_mul_lo_u32 v3, v1, v2
	v_sub_u32_e32 v3, v5, v3
	v_add_u32_e32 v4, 1, v1
	v_cmp_ge_u32_e32 vcc, v3, v2
	s_nop 1
	v_cndmask_b32_e32 v1, v1, v4, vcc
	v_sub_u32_e32 v4, v3, v2
	v_cndmask_b32_e32 v3, v3, v4, vcc
	v_add_u32_e32 v4, 1, v1
	v_cmp_ge_u32_e32 vcc, v3, v2
	v_add_u32_e32 v3, 1, v5
	s_nop 0
	v_cndmask_b32_e32 v1, v1, v4, vcc
	v_mul_lo_u32 v4, v2, v1
	v_add_u32_e32 v2, v4, v2
	v_cmp_ne_u32_e32 vcc, v3, v2
	s_and_saveexec_b64 s[4:5], vcc
	s_xor_b64 s[4:5], exec, s[4:5]
	s_cbranch_execz .LBB0_72
	s_waitcnt lgkmcnt(0)
	s_add_u32 s10, s80, 0x1d83500
	s_addc_u32 s11, s81, 0
	v_mov_b32_e32 v0, 0
	global_load_dword v0, v0, s[10:11] sc1
	s_waitcnt vmcnt(0)
	v_cmp_eq_u32_e32 vcc, 0, v0
	s_and_saveexec_b64 s[6:7], vcc
	s_cbranch_execz .LBB0_71
	s_add_u32 s8, s80, 0x1d80200
	s_addc_u32 s9, s81, 0
	s_mov_b32 s22, 1
	s_mov_b64 s[12:13], 0
	v_mov_b32_e32 v0, 0
	s_branch .LBB0_62

; DI unsigned xb_ld(unsigned* p)              { return __hip_atomic_load(p, __ATOMIC_RELAXED, __HIP_MEMORY_SCOPE_AGENT); }
; DI unsigned xb_add(unsigned* p, unsigned v) { return __hip_atomic_fetch_add(p, v, __ATOMIC_RELAXED, __HIP_MEMORY_SCOPE_AGENT); }
; #define XB_SPIN(cond, bar) do { unsigned _sp = 0; while (cond) { __builtin_amdgcn_s_sleep(1); \
;     if ((++_sp & 255u) == 0u) { if (xb_ld(&(bar)[XB_TMO])) break; if (_sp > XB_SPIN_CAP) { atomicAdd(&(bar)[XB_TMO], 1u); break; } } } } while (0)
; DI void xcd_barrier(const XcdBarrier& b, const int wid_s) {
;     ...
;             else XB_SPIN(xb_ld(&bar[XB_TOPGEN]) == tg, bar);
;             __builtin_amdgcn_fence(__ATOMIC_ACQUIRE, "agent");
;             xb_add(&bar[XB_XGEN(b.x)], 1u);
;             asm volatile("s_waitcnt vmcnt(0)" ::: "memory");
;         } else {
;             XB_SPIN(xb_ld(&bar[XB_XGEN(b.x)]) == gen, bar);
.LBB0_66:
	global_load_dword v2, v0, s[10:11] sc1
	s_add_i32 s22, s22, 1
	s_mov_b64 s[18:19], -1
	s_waitcnt vmcnt(0)
	v_cmp_ne_u32_e32 vcc, 0, v2
	s_orn2_b64 s[16:17], vcc, exec
	s_branch .LBB0_61

; DI unsigned xb_ld(unsigned* p)              { return __hip_atomic_load(p, __ATOMIC_RELAXED, __HIP_MEMORY_SCOPE_AGENT); }
; DI unsigned xb_add(unsigned* p, unsigned v) { return __hip_atomic_fetch_add(p, v, __ATOMIC_RELAXED, __HIP_MEMORY_SCOPE_AGENT); }
; #define XB_SPIN(cond, bar) do { unsigned _sp = 0; while (cond) { __builtin_amdgcn_s_sleep(1); \
;     if ((++_sp & 255u) == 0u) { if (xb_ld(&(bar)[XB_TMO])) break; if (_sp > XB_SPIN_CAP) { atomicAdd(&(bar)[XB_TMO], 1u); break; } } } } while (0)
; DI void xcd_barrier(const XcdBarrier& b, const int wid_s) {
;     ...
;             __builtin_amdgcn_fence(__ATOMIC_RELEASE, "agent");
;             asm volatile("s_waitcnt vmcnt(0)" ::: "memory");
;             const unsigned og = xb_add(&bar[XB_TOP], 1u);
;             const unsigned tg = og / nx;
;             if (og + 1u == (tg + 1u) * nx) xb_add(&bar[XB_TOPGEN], 1u);
;             else XB_SPIN(xb_ld(&bar[XB_TOPGEN]) == tg, bar);
;             __builtin_amdgcn_fence(__ATOMIC_ACQUIRE, "agent");
;             xb_add(&bar[XB_XGEN(b.x)], 1u);
;             asm volatile("s_waitcnt vmcnt(0)" ::: "memory");
.LBB0_89:
	s_or_b64 exec, exec, s[4:5]
	s_mov_b64 s[4:5], exec
	v_mbcnt_lo_u32_b32 v0, s4, 0
	v_mbcnt_hi_u32_b32 v0, s5, v0
	v_cmp_eq_u32_e32 vcc, 0, v0
	s_waitcnt vmcnt(0)
	buffer_inv sc1
	s_and_saveexec_b64 s[6:7], vcc
	s_cbranch_execz .LBB0_91
	s_bcnt1_i32_b64 s4, s[4:5]
.LBB0_91:
	s_or_b64 exec, exec, s[6:7]
	s_waitcnt vmcnt(0)

; DI int fresh_tid(int wid_s) { int l; asm volatile("v_mbcnt_lo_u32_b32 %0, -1, 0\n\tv_mbcnt_hi_u32_b32 %0, -1, %0" : "=v"(l)); return wid_s * 64 + l; }
; DI unsigned xb_ld(unsigned* p)              { return __hip_atomic_load(p, __ATOMIC_RELAXED, __HIP_MEMORY_SCOPE_AGENT); }
; DI unsigned xb_add(unsigned* p, unsigned v) { return __hip_atomic_fetch_add(p, v, __ATOMIC_RELAXED, __HIP_MEMORY_SCOPE_AGENT); }
; #define XB_SPIN(cond, bar) do { unsigned _sp = 0; while (cond) { __builtin_amdgcn_s_sleep(1); \
;     if ((++_sp & 255u) == 0u) { if (xb_ld(&(bar)[XB_TMO])) break; if (_sp > XB_SPIN_CAP) { atomicAdd(&(bar)[XB_TMO], 1u); break; } } } } while (0)
; DI void xcd_barrier(const XcdBarrier& b, const int wid_s) {
;     ...
;     if (fresh_tid(wid_s) == 0) {
;         unsigned* bar = b.bar;
;         __builtin_amdgcn_s_waitcnt(0);
;         unsigned nloc = b.st[0], nx = b.st[1];
;         if (nloc == 0u) { xcd_barrier_complete(bar, b.x, nloc, nx); b.st[0] = nloc; b.st[1] = nx; }
;         const unsigned old = xb_add(&bar[XB_XSUB(b.x)], 1u);
;         const unsigned gen = old / nloc;
;         if (old + 1u == (gen + 1u) * nloc) {
;             __builtin_amdgcn_fence(__ATOMIC_RELEASE, "agent");
;             asm volatile("s_waitcnt vmcnt(0)" ::: "memory");
;             const unsigned og = xb_add(&bar[XB_TOP], 1u);
;             const unsigned tg = og / nx;
;             if (og + 1u == (tg + 1u) * nx) xb_add(&bar[XB_TOPGEN], 1u);
;             else XB_SPIN(xb_ld(&bar[XB_TOPGEN]) == tg, bar);
;             __builtin_amdgcn_fence(__ATOMIC_ACQUIRE, "agent");
;             xb_add(&bar[XB_XGEN(b.x)], 1u);
;             asm volatile("s_waitcnt vmcnt(0)" ::: "memory");
;         } else {
;             XB_SPIN(xb_ld(&bar[XB_XGEN(b.x)]) == gen, bar);
.LBB0_182:
	s_or_b64 exec, exec, s[6:7]
	v_cvt_f32_u32_e32 v4, v2
	s_waitcnt vmcnt(0)
	v_readfirstlane_b32 s4, v3
	v_sub_u32_e32 v3, 0, v2
	v_rcp_iflag_f32_e32 v4, v4
	v_add_u32_e32 v5, s4, v1
	v_mul_f32_e32 v4, 0x4f7ffffe, v4
	v_cvt_u32_f32_e32 v4, v4
	v_mul_lo_u32 v1, v3, v4
	v_mul_hi_u32 v1, v4, v1
	v_add_u32_e32 v1, v4, v1
	v_mul_hi_u32 v1, v5, v1
	v_mul_lo_u32 v3, v1, v2
	v_sub_u32_e32 v3, v5, v3
	v_add_u32_e32 v4, 1, v1
	v_cmp_ge_u32_e32 vcc, v3, v2
	s_nop 1
	v_cndmask_b32_e32 v1, v1, v4, vcc
	v_sub_u32_e32 v4, v3, v2
	v_cndmask_b32_e32 v3, v3, v4, vcc
	v_add_u32_e32 v4, 1, v1
	v_cmp_ge_u32_e32 vcc, v3, v2
	v_add_u32_e32 v3, 1, v5
	s_nop 0
	v_cndmask_b32_e32 v1, v1, v4, vcc
	v_mul_lo_u32 v4, v2, v1
	v_add_u32_e32 v2, v4, v2
	v_cmp_ne_u32_e32 vcc, v3, v2
	s_and_saveexec_b64 s[4:5], vcc
	s_xor_b64 s[4:5], exec, s[4:5]
	s_cbranch_execz .LBB0_196
	s_waitcnt lgkmcnt(0)
	s_add_u32 s10, s80, 0x1d83500
	s_addc_u32 s11, s81, 0
	v_mov_b32_e32 v0, 0
	global_load_dword v0, v0, s[10:11] sc1
	s_waitcnt vmcnt(0)
	v_cmp_eq_u32_e32 vcc, 1, v0
	s_and_saveexec_b64 s[6:7], vcc
	s_cbranch_execz .LBB0_195
	s_add_u32 s8, s80, 0x1d80200
	s_addc_u32 s9, s81, 0
	s_mov_b32 s22, 1
	s_mov_b64 s[12:13], 0
	v_mov_b32_e32 v0, 0
	s_branch .LBB0_186

; DI unsigned xb_ld(unsigned* p)              { return __hip_atomic_load(p, __ATOMIC_RELAXED, __HIP_MEMORY_SCOPE_AGENT); }
; DI unsigned xb_add(unsigned* p, unsigned v) { return __hip_atomic_fetch_add(p, v, __ATOMIC_RELAXED, __HIP_MEMORY_SCOPE_AGENT); }
; #define XB_SPIN(cond, bar) do { unsigned _sp = 0; while (cond) { __builtin_amdgcn_s_sleep(1); \
;     if ((++_sp & 255u) == 0u) { if (xb_ld(&(bar)[XB_TMO])) break; if (_sp > XB_SPIN_CAP) { atomicAdd(&(bar)[XB_TMO], 1u); break; } } } } while (0)
; DI void xcd_barrier(const XcdBarrier& b, const int wid_s) {
;     ...
;             else XB_SPIN(xb_ld(&bar[XB_TOPGEN]) == tg, bar);
;             __builtin_amdgcn_fence(__ATOMIC_ACQUIRE, "agent");
;             xb_add(&bar[XB_XGEN(b.x)], 1u);
;             asm volatile("s_waitcnt vmcnt(0)" ::: "memory");
;         } else {
;             XB_SPIN(xb_ld(&bar[XB_XGEN(b.x)]) == gen, bar);
.LBB0_190:
	global_load_dword v2, v0, s[10:11] sc1
	s_add_i32 s22, s22, 1
	s_mov_b64 s[18:19], -1
	s_waitcnt vmcnt(0)
	v_cmp_ne_u32_e32 vcc, 1, v2
	s_orn2_b64 s[16:17], vcc, exec
	s_branch .LBB0_185

; DI unsigned xb_ld(unsigned* p)              { return __hip_atomic_load(p, __ATOMIC_RELAXED, __HIP_MEMORY_SCOPE_AGENT); }
; DI unsigned xb_add(unsigned* p, unsigned v) { return __hip_atomic_fetch_add(p, v, __ATOMIC_RELAXED, __HIP_MEMORY_SCOPE_AGENT); }
; #define XB_SPIN(cond, bar) do { unsigned _sp = 0; while (cond) { __builtin_amdgcn_s_sleep(1); \
;     if ((++_sp & 255u) == 0u) { if (xb_ld(&(bar)[XB_TMO])) break; if (_sp > XB_SPIN_CAP) { atomicAdd(&(bar)[XB_TMO], 1u); break; } } } } while (0)
; DI void xcd_barrier(const XcdBarrier& b, const int wid_s) {
;     ...
;             __builtin_amdgcn_fence(__ATOMIC_RELEASE, "agent");
;             asm volatile("s_waitcnt vmcnt(0)" ::: "memory");
;             const unsigned og = xb_add(&bar[XB_TOP], 1u);
;             const unsigned tg = og / nx;
;             if (og + 1u == (tg + 1u) * nx) xb_add(&bar[XB_TOPGEN], 1u);
;             else XB_SPIN(xb_ld(&bar[XB_TOPGEN]) == tg, bar);
;             __builtin_amdgcn_fence(__ATOMIC_ACQUIRE, "agent");
;             xb_add(&bar[XB_XGEN(b.x)], 1u);
;             asm volatile("s_waitcnt vmcnt(0)" ::: "memory");
.LBB0_213:
	s_or_b64 exec, exec, s[4:5]
	s_mov_b64 s[4:5], exec
	v_mbcnt_lo_u32_b32 v0, s4, 0
	v_mbcnt_hi_u32_b32 v0, s5, v0
	v_cmp_eq_u32_e32 vcc, 0, v0
	s_waitcnt vmcnt(0)
	buffer_inv sc1
	s_and_saveexec_b64 s[6:7], vcc
	s_cbranch_execz .LBB0_215
	s_bcnt1_i32_b64 s4, s[4:5]
.LBB0_215:
	s_or_b64 exec, exec, s[6:7]
	s_waitcnt vmcnt(0)

; DI int fresh_tid(int wid_s) { int l; asm volatile("v_mbcnt_lo_u32_b32 %0, -1, 0\n\tv_mbcnt_hi_u32_b32 %0, -1, %0" : "=v"(l)); return wid_s * 64 + l; }
; DI unsigned xb_ld(unsigned* p)              { return __hip_atomic_load(p, __ATOMIC_RELAXED, __HIP_MEMORY_SCOPE_AGENT); }
; DI unsigned xb_add(unsigned* p, unsigned v) { return __hip_atomic_fetch_add(p, v, __ATOMIC_RELAXED, __HIP_MEMORY_SCOPE_AGENT); }
; #define XB_SPIN(cond, bar) do { unsigned _sp = 0; while (cond) { __builtin_amdgcn_s_sleep(1); \
;     if ((++_sp & 255u) == 0u) { if (xb_ld(&(bar)[XB_TMO])) break; if (_sp > XB_SPIN_CAP) { atomicAdd(&(bar)[XB_TMO], 1u); break; } } } } while (0)
; DI void xcd_barrier(const XcdBarrier& b, const int wid_s) {
;     ...
;     if (fresh_tid(wid_s) == 0) {
;         unsigned* bar = b.bar;
;         __builtin_amdgcn_s_waitcnt(0);
;         unsigned nloc = b.st[0], nx = b.st[1];
;         if (nloc == 0u) { xcd_barrier_complete(bar, b.x, nloc, nx); b.st[0] = nloc; b.st[1] = nx; }
;         const unsigned old = xb_add(&bar[XB_XSUB(b.x)], 1u);
;         const unsigned gen = old / nloc;
;         if (old + 1u == (gen + 1u) * nloc) {
;             __builtin_amdgcn_fence(__ATOMIC_RELEASE, "agent");
;             asm volatile("s_waitcnt vmcnt(0)" ::: "memory");
;             const unsigned og = xb_add(&bar[XB_TOP], 1u);
;             const unsigned tg = og / nx;
;             if (og + 1u == (tg + 1u) * nx) xb_add(&bar[XB_TOPGEN], 1u);
;             else XB_SPIN(xb_ld(&bar[XB_TOPGEN]) == tg, bar);
;             __builtin_amdgcn_fence(__ATOMIC_ACQUIRE, "agent");
;             xb_add(&bar[XB_XGEN(b.x)], 1u);
;             asm volatile("s_waitcnt vmcnt(0)" ::: "memory");
;         } else {
;             XB_SPIN(xb_ld(&bar[XB_XGEN(b.x)]) == gen, bar);
.LBB0_495:
	s_or_b64 exec, exec, s[6:7]
	v_cvt_f32_u32_e32 v4, v2
	s_waitcnt vmcnt(0)
	v_readfirstlane_b32 s4, v3
	v_sub_u32_e32 v3, 0, v2
	v_rcp_iflag_f32_e32 v4, v4
	v_add_u32_e32 v5, s4, v1
	v_mul_f32_e32 v4, 0x4f7ffffe, v4
	v_cvt_u32_f32_e32 v4, v4
	v_mul_lo_u32 v1, v3, v4
	v_mul_hi_u32 v1, v4, v1
	v_add_u32_e32 v1, v4, v1
	v_mul_hi_u32 v1, v5, v1
	v_mul_lo_u32 v3, v1, v2
	v_sub_u32_e32 v3, v5, v3
	v_add_u32_e32 v4, 1, v1
	v_cmp_ge_u32_e32 vcc, v3, v2
	s_nop 1
	v_cndmask_b32_e32 v1, v1, v4, vcc
	v_sub_u32_e32 v4, v3, v2
	v_cndmask_b32_e32 v3, v3, v4, vcc
	v_add_u32_e32 v4, 1, v1
	v_cmp_ge_u32_e32 vcc, v3, v2
	v_add_u32_e32 v3, 1, v5
	s_nop 0
	v_cndmask_b32_e32 v1, v1, v4, vcc
	v_mul_lo_u32 v4, v2, v1
	v_add_u32_e32 v2, v4, v2
	v_cmp_ne_u32_e32 vcc, v3, v2
	s_and_saveexec_b64 s[4:5], vcc
	s_xor_b64 s[4:5], exec, s[4:5]
	s_cbranch_execz .LBB0_509
	s_waitcnt lgkmcnt(0)
	s_add_u32 s10, s80, 0x1d83500
	s_addc_u32 s11, s81, 0
	v_mov_b32_e32 v0, 0
	global_load_dword v0, v0, s[10:11] sc1
	s_waitcnt vmcnt(0)
	v_cmp_eq_u32_e32 vcc, 2, v0
	s_and_saveexec_b64 s[6:7], vcc
	s_cbranch_execz .LBB0_508
	s_add_u32 s8, s80, 0x1d80200
	s_addc_u32 s9, s81, 0
	s_mov_b32 s22, 1
	s_mov_b64 s[12:13], 0
	v_mov_b32_e32 v0, 0
	s_branch .LBB0_499

; DI unsigned xb_ld(unsigned* p)              { return __hip_atomic_load(p, __ATOMIC_RELAXED, __HIP_MEMORY_SCOPE_AGENT); }
; DI unsigned xb_add(unsigned* p, unsigned v) { return __hip_atomic_fetch_add(p, v, __ATOMIC_RELAXED, __HIP_MEMORY_SCOPE_AGENT); }
; #define XB_SPIN(cond, bar) do { unsigned _sp = 0; while (cond) { __builtin_amdgcn_s_sleep(1); \
;     if ((++_sp & 255u) == 0u) { if (xb_ld(&(bar)[XB_TMO])) break; if (_sp > XB_SPIN_CAP) { atomicAdd(&(bar)[XB_TMO], 1u); break; } } } } while (0)
; DI void xcd_barrier(const XcdBarrier& b, const int wid_s) {
;     ...
;             else XB_SPIN(xb_ld(&bar[XB_TOPGEN]) == tg, bar);
;             __builtin_amdgcn_fence(__ATOMIC_ACQUIRE, "agent");
;             xb_add(&bar[XB_XGEN(b.x)], 1u);
;             asm volatile("s_waitcnt vmcnt(0)" ::: "memory");
;         } else {
;             XB_SPIN(xb_ld(&bar[XB_XGEN(b.x)]) == gen, bar);
.LBB0_503:
	global_load_dword v2, v0, s[10:11] sc1
	s_add_i32 s22, s22, 1
	s_mov_b64 s[18:19], -1
	s_waitcnt vmcnt(0)
	v_cmp_ne_u32_e32 vcc, 2, v2
	s_orn2_b64 s[16:17], vcc, exec
	s_branch .LBB0_498

; DI unsigned xb_ld(unsigned* p)              { return __hip_atomic_load(p, __ATOMIC_RELAXED, __HIP_MEMORY_SCOPE_AGENT); }
; DI unsigned xb_add(unsigned* p, unsigned v) { return __hip_atomic_fetch_add(p, v, __ATOMIC_RELAXED, __HIP_MEMORY_SCOPE_AGENT); }
; #define XB_SPIN(cond, bar) do { unsigned _sp = 0; while (cond) { __builtin_amdgcn_s_sleep(1); \
;     if ((++_sp & 255u) == 0u) { if (xb_ld(&(bar)[XB_TMO])) break; if (_sp > XB_SPIN_CAP) { atomicAdd(&(bar)[XB_TMO], 1u); break; } } } } while (0)
; DI void xcd_barrier(const XcdBarrier& b, const int wid_s) {
;     ...
;             __builtin_amdgcn_fence(__ATOMIC_RELEASE, "agent");
;             asm volatile("s_waitcnt vmcnt(0)" ::: "memory");
;             const unsigned og = xb_add(&bar[XB_TOP], 1u);
;             const unsigned tg = og / nx;
;             if (og + 1u == (tg + 1u) * nx) xb_add(&bar[XB_TOPGEN], 1u);
;             else XB_SPIN(xb_ld(&bar[XB_TOPGEN]) == tg, bar);
;             __builtin_amdgcn_fence(__ATOMIC_ACQUIRE, "agent");
;             xb_add(&bar[XB_XGEN(b.x)], 1u);
;             asm volatile("s_waitcnt vmcnt(0)" ::: "memory");
.LBB0_526:
	s_or_b64 exec, exec, s[4:5]
	s_mov_b64 s[4:5], exec
	v_mbcnt_lo_u32_b32 v0, s4, 0
	v_mbcnt_hi_u32_b32 v0, s5, v0
	v_cmp_eq_u32_e32 vcc, 0, v0
	s_waitcnt vmcnt(0)
	buffer_inv sc1
	s_and_saveexec_b64 s[6:7], vcc
	s_cbranch_execz .LBB0_528
	s_bcnt1_i32_b64 s4, s[4:5]
.LBB0_528:
	s_or_b64 exec, exec, s[6:7]
	s_waitcnt vmcnt(0)

; DI int fresh_tid(int wid_s) { int l; asm volatile("v_mbcnt_lo_u32_b32 %0, -1, 0\n\tv_mbcnt_hi_u32_b32 %0, -1, %0" : "=v"(l)); return wid_s * 64 + l; }
; DI unsigned xb_ld(unsigned* p)              { return __hip_atomic_load(p, __ATOMIC_RELAXED, __HIP_MEMORY_SCOPE_AGENT); }
; DI unsigned xb_add(unsigned* p, unsigned v) { return __hip_atomic_fetch_add(p, v, __ATOMIC_RELAXED, __HIP_MEMORY_SCOPE_AGENT); }
; #define XB_SPIN(cond, bar) do { unsigned _sp = 0; while (cond) { __builtin_amdgcn_s_sleep(1); \
;     if ((++_sp & 255u) == 0u) { if (xb_ld(&(bar)[XB_TMO])) break; if (_sp > XB_SPIN_CAP) { atomicAdd(&(bar)[XB_TMO], 1u); break; } } } } while (0)
; DI void xcd_barrier(const XcdBarrier& b, const int wid_s) {
;     ...
;     if (fresh_tid(wid_s) == 0) {
;         unsigned* bar = b.bar;
;         __builtin_amdgcn_s_waitcnt(0);
;         unsigned nloc = b.st[0], nx = b.st[1];
;         if (nloc == 0u) { xcd_barrier_complete(bar, b.x, nloc, nx); b.st[0] = nloc; b.st[1] = nx; }
;         const unsigned old = xb_add(&bar[XB_XSUB(b.x)], 1u);
;         const unsigned gen = old / nloc;
;         if (old + 1u == (gen + 1u) * nloc) {
;             __builtin_amdgcn_fence(__ATOMIC_RELEASE, "agent");
;             asm volatile("s_waitcnt vmcnt(0)" ::: "memory");
;             const unsigned og = xb_add(&bar[XB_TOP], 1u);
;             const unsigned tg = og / nx;
;             if (og + 1u == (tg + 1u) * nx) xb_add(&bar[XB_TOPGEN], 1u);
;             else XB_SPIN(xb_ld(&bar[XB_TOPGEN]) == tg, bar);
;             __builtin_amdgcn_fence(__ATOMIC_ACQUIRE, "agent");
;             xb_add(&bar[XB_XGEN(b.x)], 1u);
;             asm volatile("s_waitcnt vmcnt(0)" ::: "memory");
;         } else {
;             XB_SPIN(xb_ld(&bar[XB_XGEN(b.x)]) == gen, bar);
.LBB0_609:
	s_or_b64 exec, exec, s[6:7]
	v_cvt_f32_u32_e32 v4, v2
	s_waitcnt vmcnt(0)
	v_readfirstlane_b32 s4, v3
	v_sub_u32_e32 v3, 0, v2
	v_rcp_iflag_f32_e32 v4, v4
	v_add_u32_e32 v5, s4, v1
	v_mul_f32_e32 v4, 0x4f7ffffe, v4
	v_cvt_u32_f32_e32 v4, v4
	v_mul_lo_u32 v1, v3, v4
	v_mul_hi_u32 v1, v4, v1
	v_add_u32_e32 v1, v4, v1
	v_mul_hi_u32 v1, v5, v1
	v_mul_lo_u32 v3, v1, v2
	v_sub_u32_e32 v3, v5, v3
	v_add_u32_e32 v4, 1, v1
	v_cmp_ge_u32_e32 vcc, v3, v2
	s_nop 1
	v_cndmask_b32_e32 v1, v1, v4, vcc
	v_sub_u32_e32 v4, v3, v2
	v_cndmask_b32_e32 v3, v3, v4, vcc
	v_add_u32_e32 v4, 1, v1
	v_cmp_ge_u32_e32 vcc, v3, v2
	v_add_u32_e32 v3, 1, v5
	s_nop 0
	v_cndmask_b32_e32 v1, v1, v4, vcc
	v_mul_lo_u32 v4, v2, v1
	v_add_u32_e32 v2, v4, v2
	v_cmp_ne_u32_e32 vcc, v3, v2
	s_and_saveexec_b64 s[4:5], vcc
	s_xor_b64 s[4:5], exec, s[4:5]
	s_cbranch_execz .LBB0_623
	s_waitcnt lgkmcnt(0)
	s_add_u32 s10, s80, 0x1d83500
	s_addc_u32 s11, s81, 0
	v_mov_b32_e32 v0, 0
	global_load_dword v0, v0, s[10:11] sc1
	s_waitcnt vmcnt(0)
	v_cmp_eq_u32_e32 vcc, 3, v0
	s_and_saveexec_b64 s[6:7], vcc
	s_cbranch_execz .LBB0_622
	s_add_u32 s8, s80, 0x1d80200
	s_addc_u32 s9, s81, 0
	s_mov_b32 s22, 1
	s_mov_b64 s[12:13], 0
	v_mov_b32_e32 v0, 0
	s_branch .LBB0_613

; DI unsigned xb_ld(unsigned* p)              { return __hip_atomic_load(p, __ATOMIC_RELAXED, __HIP_MEMORY_SCOPE_AGENT); }
; DI unsigned xb_add(unsigned* p, unsigned v) { return __hip_atomic_fetch_add(p, v, __ATOMIC_RELAXED, __HIP_MEMORY_SCOPE_AGENT); }
; #define XB_SPIN(cond, bar) do { unsigned _sp = 0; while (cond) { __builtin_amdgcn_s_sleep(1); \
;     if ((++_sp & 255u) == 0u) { if (xb_ld(&(bar)[XB_TMO])) break; if (_sp > XB_SPIN_CAP) { atomicAdd(&(bar)[XB_TMO], 1u); break; } } } } while (0)
; DI void xcd_barrier(const XcdBarrier& b, const int wid_s) {
;     ...
;             else XB_SPIN(xb_ld(&bar[XB_TOPGEN]) == tg, bar);
;             __builtin_amdgcn_fence(__ATOMIC_ACQUIRE, "agent");
;             xb_add(&bar[XB_XGEN(b.x)], 1u);
;             asm volatile("s_waitcnt vmcnt(0)" ::: "memory");
;         } else {
;             XB_SPIN(xb_ld(&bar[XB_XGEN(b.x)]) == gen, bar);
.LBB0_617:
	global_load_dword v2, v0, s[10:11] sc1
	s_add_i32 s22, s22, 1
	s_mov_b64 s[18:19], -1
	s_waitcnt vmcnt(0)
	v_cmp_ne_u32_e32 vcc, 3, v2
	s_orn2_b64 s[16:17], vcc, exec
	s_branch .LBB0_612

; DI unsigned xb_ld(unsigned* p)              { return __hip_atomic_load(p, __ATOMIC_RELAXED, __HIP_MEMORY_SCOPE_AGENT); }
; DI unsigned xb_add(unsigned* p, unsigned v) { return __hip_atomic_fetch_add(p, v, __ATOMIC_RELAXED, __HIP_MEMORY_SCOPE_AGENT); }
; #define XB_SPIN(cond, bar) do { unsigned _sp = 0; while (cond) { __builtin_amdgcn_s_sleep(1); \
;     if ((++_sp & 255u) == 0u) { if (xb_ld(&(bar)[XB_TMO])) break; if (_sp > XB_SPIN_CAP) { atomicAdd(&(bar)[XB_TMO], 1u); break; } } } } while (0)
; DI void xcd_barrier(const XcdBarrier& b, const int wid_s) {
;     ...
;             __builtin_amdgcn_fence(__ATOMIC_RELEASE, "agent");
;             asm volatile("s_waitcnt vmcnt(0)" ::: "memory");
;             const unsigned og = xb_add(&bar[XB_TOP], 1u);
;             const unsigned tg = og / nx;
;             if (og + 1u == (tg + 1u) * nx) xb_add(&bar[XB_TOPGEN], 1u);
;             else XB_SPIN(xb_ld(&bar[XB_TOPGEN]) == tg, bar);
;             __builtin_amdgcn_fence(__ATOMIC_ACQUIRE, "agent");
;             xb_add(&bar[XB_XGEN(b.x)], 1u);
;             asm volatile("s_waitcnt vmcnt(0)" ::: "memory");
.LBB0_640:
	s_or_b64 exec, exec, s[4:5]
	s_mov_b64 s[4:5], exec
	v_mbcnt_lo_u32_b32 v0, s4, 0
	v_mbcnt_hi_u32_b32 v0, s5, v0
	v_cmp_eq_u32_e32 vcc, 0, v0
	s_waitcnt vmcnt(0)
	buffer_inv sc1
	s_and_saveexec_b64 s[6:7], vcc
	s_cbranch_execz .LBB0_642
	s_bcnt1_i32_b64 s4, s[4:5]
.LBB0_642:
	s_or_b64 exec, exec, s[6:7]
	s_waitcnt vmcnt(0)

; DI int fresh_tid(int wid_s) { int l; asm volatile("v_mbcnt_lo_u32_b32 %0, -1, 0\n\tv_mbcnt_hi_u32_b32 %0, -1, %0" : "=v"(l)); return wid_s * 64 + l; }
; DI unsigned xb_ld(unsigned* p)              { return __hip_atomic_load(p, __ATOMIC_RELAXED, __HIP_MEMORY_SCOPE_AGENT); }
; DI unsigned xb_add(unsigned* p, unsigned v) { return __hip_atomic_fetch_add(p, v, __ATOMIC_RELAXED, __HIP_MEMORY_SCOPE_AGENT); }
; #define XB_SPIN(cond, bar) do { unsigned _sp = 0; while (cond) { __builtin_amdgcn_s_sleep(1); \
;     if ((++_sp & 255u) == 0u) { if (xb_ld(&(bar)[XB_TMO])) break; if (_sp > XB_SPIN_CAP) { atomicAdd(&(bar)[XB_TMO], 1u); break; } } } } while (0)
; DI void xcd_barrier(const XcdBarrier& b, const int wid_s) {
;     ...
;     if (fresh_tid(wid_s) == 0) {
;         unsigned* bar = b.bar;
;         __builtin_amdgcn_s_waitcnt(0);
;         unsigned nloc = b.st[0], nx = b.st[1];
;         if (nloc == 0u) { xcd_barrier_complete(bar, b.x, nloc, nx); b.st[0] = nloc; b.st[1] = nx; }
;         const unsigned old = xb_add(&bar[XB_XSUB(b.x)], 1u);
;         const unsigned gen = old / nloc;
;         if (old + 1u == (gen + 1u) * nloc) {
;             __builtin_amdgcn_fence(__ATOMIC_RELEASE, "agent");
;             asm volatile("s_waitcnt vmcnt(0)" ::: "memory");
;             const unsigned og = xb_add(&bar[XB_TOP], 1u);
;             const unsigned tg = og / nx;
;             if (og + 1u == (tg + 1u) * nx) xb_add(&bar[XB_TOPGEN], 1u);
;             else XB_SPIN(xb_ld(&bar[XB_TOPGEN]) == tg, bar);
;             __builtin_amdgcn_fence(__ATOMIC_ACQUIRE, "agent");
;             xb_add(&bar[XB_XGEN(b.x)], 1u);
;             asm volatile("s_waitcnt vmcnt(0)" ::: "memory");
;         } else {
;             XB_SPIN(xb_ld(&bar[XB_XGEN(b.x)]) == gen, bar);
.LBB0_664:
	s_or_b64 exec, exec, s[6:7]
	v_cvt_f32_u32_e32 v4, v2
	s_waitcnt vmcnt(0)
	v_readfirstlane_b32 s4, v3
	v_sub_u32_e32 v3, 0, v2
	v_rcp_iflag_f32_e32 v4, v4
	v_add_u32_e32 v5, s4, v1
	v_mul_f32_e32 v4, 0x4f7ffffe, v4
	v_cvt_u32_f32_e32 v4, v4
	v_mul_lo_u32 v1, v3, v4
	v_mul_hi_u32 v1, v4, v1
	v_add_u32_e32 v1, v4, v1
	v_mul_hi_u32 v1, v5, v1
	v_mul_lo_u32 v3, v1, v2
	v_sub_u32_e32 v3, v5, v3
	v_add_u32_e32 v4, 1, v1
	v_cmp_ge_u32_e32 vcc, v3, v2
	s_nop 1
	v_cndmask_b32_e32 v1, v1, v4, vcc
	v_sub_u32_e32 v4, v3, v2
	v_cndmask_b32_e32 v3, v3, v4, vcc
	v_add_u32_e32 v4, 1, v1
	v_cmp_ge_u32_e32 vcc, v3, v2
	v_add_u32_e32 v3, 1, v5
	s_nop 0
	v_cndmask_b32_e32 v1, v1, v4, vcc
	v_mul_lo_u32 v4, v2, v1
	v_add_u32_e32 v2, v4, v2
	v_cmp_ne_u32_e32 vcc, v3, v2
	s_and_saveexec_b64 s[4:5], vcc
	s_xor_b64 s[4:5], exec, s[4:5]
	s_cbranch_execz .LBB0_678
	s_waitcnt lgkmcnt(0)
	s_add_u32 s10, s80, 0x1d83500
	s_addc_u32 s11, s81, 0
	v_mov_b32_e32 v0, 0
	global_load_dword v0, v0, s[10:11] sc1
	s_waitcnt vmcnt(0)
	v_cmp_eq_u32_e32 vcc, 4, v0
	s_and_saveexec_b64 s[6:7], vcc
	s_cbranch_execz .LBB0_677
	s_add_u32 s8, s80, 0x1d80200
	s_addc_u32 s9, s81, 0
	s_mov_b32 s22, 1
	s_mov_b64 s[12:13], 0
	v_mov_b32_e32 v0, 0
	s_branch .LBB0_668

; DI unsigned xb_ld(unsigned* p)              { return __hip_atomic_load(p, __ATOMIC_RELAXED, __HIP_MEMORY_SCOPE_AGENT); }
; DI unsigned xb_add(unsigned* p, unsigned v) { return __hip_atomic_fetch_add(p, v, __ATOMIC_RELAXED, __HIP_MEMORY_SCOPE_AGENT); }
; #define XB_SPIN(cond, bar) do { unsigned _sp = 0; while (cond) { __builtin_amdgcn_s_sleep(1); \
;     if ((++_sp & 255u) == 0u) { if (xb_ld(&(bar)[XB_TMO])) break; if (_sp > XB_SPIN_CAP) { atomicAdd(&(bar)[XB_TMO], 1u); break; } } } } while (0)
; DI void xcd_barrier(const XcdBarrier& b, const int wid_s) {
;     ...
;             else XB_SPIN(xb_ld(&bar[XB_TOPGEN]) == tg, bar);
;             __builtin_amdgcn_fence(__ATOMIC_ACQUIRE, "agent");
;             xb_add(&bar[XB_XGEN(b.x)], 1u);
;             asm volatile("s_waitcnt vmcnt(0)" ::: "memory");
;         } else {
;             XB_SPIN(xb_ld(&bar[XB_XGEN(b.x)]) == gen, bar);
.LBB0_672:
	global_load_dword v2, v0, s[10:11] sc1
	s_add_i32 s22, s22, 1
	s_mov_b64 s[18:19], -1
	s_waitcnt vmcnt(0)
	v_cmp_ne_u32_e32 vcc, 4, v2
	s_orn2_b64 s[16:17], vcc, exec
	s_branch .LBB0_667

; DI unsigned xb_ld(unsigned* p)              { return __hip_atomic_load(p, __ATOMIC_RELAXED, __HIP_MEMORY_SCOPE_AGENT); }
; DI unsigned xb_add(unsigned* p, unsigned v) { return __hip_atomic_fetch_add(p, v, __ATOMIC_RELAXED, __HIP_MEMORY_SCOPE_AGENT); }
; #define XB_SPIN(cond, bar) do { unsigned _sp = 0; while (cond) { __builtin_amdgcn_s_sleep(1); \
;     if ((++_sp & 255u) == 0u) { if (xb_ld(&(bar)[XB_TMO])) break; if (_sp > XB_SPIN_CAP) { atomicAdd(&(bar)[XB_TMO], 1u); break; } } } } while (0)
; DI void xcd_barrier(const XcdBarrier& b, const int wid_s) {
;     ...
;             __builtin_amdgcn_fence(__ATOMIC_RELEASE, "agent");
;             asm volatile("s_waitcnt vmcnt(0)" ::: "memory");
;             const unsigned og = xb_add(&bar[XB_TOP], 1u);
;             const unsigned tg = og / nx;
;             if (og + 1u == (tg + 1u) * nx) xb_add(&bar[XB_TOPGEN], 1u);
;             else XB_SPIN(xb_ld(&bar[XB_TOPGEN]) == tg, bar);
;             __builtin_amdgcn_fence(__ATOMIC_ACQUIRE, "agent");
;             xb_add(&bar[XB_XGEN(b.x)], 1u);
;             asm volatile("s_waitcnt vmcnt(0)" ::: "memory");
.LBB0_695:
	s_or_b64 exec, exec, s[4:5]
	s_mov_b64 s[4:5], exec
	v_mbcnt_lo_u32_b32 v0, s4, 0
	v_mbcnt_hi_u32_b32 v0, s5, v0
	v_cmp_eq_u32_e32 vcc, 0, v0
	s_waitcnt vmcnt(0)
	buffer_inv sc1
	s_and_saveexec_b64 s[6:7], vcc
	s_cbranch_execz .LBB0_697
	s_bcnt1_i32_b64 s4, s[4:5]
.LBB0_697:
	s_or_b64 exec, exec, s[6:7]
	s_waitcnt vmcnt(0)

; DI int fresh_tid(int wid_s) { int l; asm volatile("v_mbcnt_lo_u32_b32 %0, -1, 0\n\tv_mbcnt_hi_u32_b32 %0, -1, %0" : "=v"(l)); return wid_s * 64 + l; }
; DI unsigned xb_ld(unsigned* p)              { return __hip_atomic_load(p, __ATOMIC_RELAXED, __HIP_MEMORY_SCOPE_AGENT); }
; DI unsigned xb_add(unsigned* p, unsigned v) { return __hip_atomic_fetch_add(p, v, __ATOMIC_RELAXED, __HIP_MEMORY_SCOPE_AGENT); }
; #define XB_SPIN(cond, bar) do { unsigned _sp = 0; while (cond) { __builtin_amdgcn_s_sleep(1); \
;     if ((++_sp & 255u) == 0u) { if (xb_ld(&(bar)[XB_TMO])) break; if (_sp > XB_SPIN_CAP) { atomicAdd(&(bar)[XB_TMO], 1u); break; } } } } while (0)
; DI void xcd_barrier(const XcdBarrier& b, const int wid_s) {
;     ...
;     if (fresh_tid(wid_s) == 0) {
;         unsigned* bar = b.bar;
;         __builtin_amdgcn_s_waitcnt(0);
;         unsigned nloc = b.st[0], nx = b.st[1];
;         if (nloc == 0u) { xcd_barrier_complete(bar, b.x, nloc, nx); b.st[0] = nloc; b.st[1] = nx; }
;         const unsigned old = xb_add(&bar[XB_XSUB(b.x)], 1u);
;         const unsigned gen = old / nloc;
;         if (old + 1u == (gen + 1u) * nloc) {
;             __builtin_amdgcn_fence(__ATOMIC_RELEASE, "agent");
;             asm volatile("s_waitcnt vmcnt(0)" ::: "memory");
;             const unsigned og = xb_add(&bar[XB_TOP], 1u);
;             const unsigned tg = og / nx;
;             if (og + 1u == (tg + 1u) * nx) xb_add(&bar[XB_TOPGEN], 1u);
;             else XB_SPIN(xb_ld(&bar[XB_TOPGEN]) == tg, bar);
;             __builtin_amdgcn_fence(__ATOMIC_ACQUIRE, "agent");
;             xb_add(&bar[XB_XGEN(b.x)], 1u);
;             asm volatile("s_waitcnt vmcnt(0)" ::: "memory");
;         } else {
;             XB_SPIN(xb_ld(&bar[XB_XGEN(b.x)]) == gen, bar);
.LBB0_772:
	s_or_b64 exec, exec, s[6:7]
	v_cvt_f32_u32_e32 v4, v2
	s_waitcnt vmcnt(0)
	v_readfirstlane_b32 s4, v3
	v_sub_u32_e32 v3, 0, v2
	v_rcp_iflag_f32_e32 v4, v4
	v_add_u32_e32 v5, s4, v1
	v_mul_f32_e32 v4, 0x4f7ffffe, v4
	v_cvt_u32_f32_e32 v4, v4
	v_mul_lo_u32 v1, v3, v4
	v_mul_hi_u32 v1, v4, v1
	v_add_u32_e32 v1, v4, v1
	v_mul_hi_u32 v1, v5, v1
	v_mul_lo_u32 v3, v1, v2
	v_sub_u32_e32 v3, v5, v3
	v_add_u32_e32 v4, 1, v1
	v_cmp_ge_u32_e32 vcc, v3, v2
	s_nop 1
	v_cndmask_b32_e32 v1, v1, v4, vcc
	v_sub_u32_e32 v4, v3, v2
	v_cndmask_b32_e32 v3, v3, v4, vcc
	v_add_u32_e32 v4, 1, v1
	v_cmp_ge_u32_e32 vcc, v3, v2
	v_add_u32_e32 v3, 1, v5
	s_nop 0
	v_cndmask_b32_e32 v1, v1, v4, vcc
	v_mul_lo_u32 v4, v2, v1
	v_add_u32_e32 v2, v4, v2
	v_cmp_ne_u32_e32 vcc, v3, v2
	s_and_saveexec_b64 s[4:5], vcc
	s_xor_b64 s[4:5], exec, s[4:5]
	s_cbranch_execz .LBB0_786
	s_waitcnt lgkmcnt(0)
	s_add_u32 s12, s80, 0x1d83500
	s_addc_u32 s13, s81, 0
	v_mov_b32_e32 v0, 0
	global_load_dword v0, v0, s[12:13] sc1
	s_waitcnt vmcnt(0)
	v_cmp_eq_u32_e32 vcc, 5, v0
	s_and_saveexec_b64 s[6:7], vcc
	s_cbranch_execz .LBB0_785
	s_add_u32 s10, s80, 0x1d80200
	s_addc_u32 s11, s81, 0
	s_mov_b32 s24, 1
	s_mov_b64 s[14:15], 0
	v_mov_b32_e32 v0, 0
	s_branch .LBB0_776

; DI unsigned xb_ld(unsigned* p)              { return __hip_atomic_load(p, __ATOMIC_RELAXED, __HIP_MEMORY_SCOPE_AGENT); }
; DI unsigned xb_add(unsigned* p, unsigned v) { return __hip_atomic_fetch_add(p, v, __ATOMIC_RELAXED, __HIP_MEMORY_SCOPE_AGENT); }
; #define XB_SPIN(cond, bar) do { unsigned _sp = 0; while (cond) { __builtin_amdgcn_s_sleep(1); \
;     if ((++_sp & 255u) == 0u) { if (xb_ld(&(bar)[XB_TMO])) break; if (_sp > XB_SPIN_CAP) { atomicAdd(&(bar)[XB_TMO], 1u); break; } } } } while (0)
; DI void xcd_barrier(const XcdBarrier& b, const int wid_s) {
;     ...
;             else XB_SPIN(xb_ld(&bar[XB_TOPGEN]) == tg, bar);
;             __builtin_amdgcn_fence(__ATOMIC_ACQUIRE, "agent");
;             xb_add(&bar[XB_XGEN(b.x)], 1u);
;             asm volatile("s_waitcnt vmcnt(0)" ::: "memory");
;         } else {
;             XB_SPIN(xb_ld(&bar[XB_XGEN(b.x)]) == gen, bar);
.LBB0_780:
	global_load_dword v2, v0, s[12:13] sc1
	s_add_i32 s24, s24, 1
	s_mov_b64 s[20:21], -1
	s_waitcnt vmcnt(0)
	v_cmp_ne_u32_e32 vcc, 5, v2
	s_orn2_b64 s[18:19], vcc, exec
	s_branch .LBB0_775

; DI unsigned xb_ld(unsigned* p)              { return __hip_atomic_load(p, __ATOMIC_RELAXED, __HIP_MEMORY_SCOPE_AGENT); }
; DI unsigned xb_add(unsigned* p, unsigned v) { return __hip_atomic_fetch_add(p, v, __ATOMIC_RELAXED, __HIP_MEMORY_SCOPE_AGENT); }
; #define XB_SPIN(cond, bar) do { unsigned _sp = 0; while (cond) { __builtin_amdgcn_s_sleep(1); \
;     if ((++_sp & 255u) == 0u) { if (xb_ld(&(bar)[XB_TMO])) break; if (_sp > XB_SPIN_CAP) { atomicAdd(&(bar)[XB_TMO], 1u); break; } } } } while (0)
; DI void xcd_barrier(const XcdBarrier& b, const int wid_s) {
;     ...
;             __builtin_amdgcn_fence(__ATOMIC_RELEASE, "agent");
;             asm volatile("s_waitcnt vmcnt(0)" ::: "memory");
;             const unsigned og = xb_add(&bar[XB_TOP], 1u);
;             const unsigned tg = og / nx;
;             if (og + 1u == (tg + 1u) * nx) xb_add(&bar[XB_TOPGEN], 1u);
;             else XB_SPIN(xb_ld(&bar[XB_TOPGEN]) == tg, bar);
;             __builtin_amdgcn_fence(__ATOMIC_ACQUIRE, "agent");
;             xb_add(&bar[XB_XGEN(b.x)], 1u);
;             asm volatile("s_waitcnt vmcnt(0)" ::: "memory");
.LBB0_803:
	s_or_b64 exec, exec, s[4:5]
	s_mov_b64 s[4:5], exec
	v_mbcnt_lo_u32_b32 v0, s4, 0
	v_mbcnt_hi_u32_b32 v0, s5, v0
	v_cmp_eq_u32_e32 vcc, 0, v0
	s_waitcnt vmcnt(0)
	buffer_inv sc1
	s_and_saveexec_b64 s[6:7], vcc
	s_cbranch_execz .LBB0_805
	s_bcnt1_i32_b64 s4, s[4:5]
.LBB0_805:
	s_or_b64 exec, exec, s[6:7]
	s_waitcnt vmcnt(0)

; DI int fresh_tid(int wid_s) { int l; asm volatile("v_mbcnt_lo_u32_b32 %0, -1, 0\n\tv_mbcnt_hi_u32_b32 %0, -1, %0" : "=v"(l)); return wid_s * 64 + l; }
; DI unsigned xb_ld(unsigned* p)              { return __hip_atomic_load(p, __ATOMIC_RELAXED, __HIP_MEMORY_SCOPE_AGENT); }
; DI unsigned xb_add(unsigned* p, unsigned v) { return __hip_atomic_fetch_add(p, v, __ATOMIC_RELAXED, __HIP_MEMORY_SCOPE_AGENT); }
; #define XB_SPIN(cond, bar) do { unsigned _sp = 0; while (cond) { __builtin_amdgcn_s_sleep(1); \
;     if ((++_sp & 255u) == 0u) { if (xb_ld(&(bar)[XB_TMO])) break; if (_sp > XB_SPIN_CAP) { atomicAdd(&(bar)[XB_TMO], 1u); break; } } } } while (0)
; DI void xcd_barrier(const XcdBarrier& b, const int wid_s) {
;     ...
;     if (fresh_tid(wid_s) == 0) {
;         unsigned* bar = b.bar;
;         __builtin_amdgcn_s_waitcnt(0);
;         unsigned nloc = b.st[0], nx = b.st[1];
;         if (nloc == 0u) { xcd_barrier_complete(bar, b.x, nloc, nx); b.st[0] = nloc; b.st[1] = nx; }
;         const unsigned old = xb_add(&bar[XB_XSUB(b.x)], 1u);
;         const unsigned gen = old / nloc;
;         if (old + 1u == (gen + 1u) * nloc) {
;             __builtin_amdgcn_fence(__ATOMIC_RELEASE, "agent");
;             asm volatile("s_waitcnt vmcnt(0)" ::: "memory");
;             const unsigned og = xb_add(&bar[XB_TOP], 1u);
;             const unsigned tg = og / nx;
;             if (og + 1u == (tg + 1u) * nx) xb_add(&bar[XB_TOPGEN], 1u);
;             else XB_SPIN(xb_ld(&bar[XB_TOPGEN]) == tg, bar);
;             __builtin_amdgcn_fence(__ATOMIC_ACQUIRE, "agent");
;             xb_add(&bar[XB_XGEN(b.x)], 1u);
;             asm volatile("s_waitcnt vmcnt(0)" ::: "memory");
;         } else {
;             XB_SPIN(xb_ld(&bar[XB_XGEN(b.x)]) == gen, bar);
.LBB0_894:
	s_or_b64 exec, exec, s[12:13]
	v_cvt_f32_u32_e32 v4, v2
	s_waitcnt vmcnt(0)
	v_readfirstlane_b32 s10, v3
	v_sub_u32_e32 v3, 0, v2
	v_rcp_iflag_f32_e32 v4, v4
	v_add_u32_e32 v5, s10, v1
	v_mul_f32_e32 v4, 0x4f7ffffe, v4
	v_cvt_u32_f32_e32 v4, v4
	v_mul_lo_u32 v1, v3, v4
	v_mul_hi_u32 v1, v4, v1
	v_add_u32_e32 v1, v4, v1
	v_mul_hi_u32 v1, v5, v1
	v_mul_lo_u32 v3, v1, v2
	v_sub_u32_e32 v3, v5, v3
	v_add_u32_e32 v4, 1, v1
	v_cmp_ge_u32_e32 vcc, v3, v2
	s_nop 1
	v_cndmask_b32_e32 v1, v1, v4, vcc
	v_sub_u32_e32 v4, v3, v2
	v_cndmask_b32_e32 v3, v3, v4, vcc
	v_add_u32_e32 v4, 1, v1
	v_cmp_ge_u32_e32 vcc, v3, v2
	v_add_u32_e32 v3, 1, v5
	s_nop 0
	v_cndmask_b32_e32 v1, v1, v4, vcc
	v_mul_lo_u32 v4, v2, v1
	v_add_u32_e32 v2, v4, v2
	v_cmp_ne_u32_e32 vcc, v3, v2
	s_and_saveexec_b64 s[10:11], vcc
	s_xor_b64 s[10:11], exec, s[10:11]
	s_cbranch_execz .LBB0_908
	s_waitcnt lgkmcnt(0)
	s_add_u32 s16, s80, 0x1d83500
	s_addc_u32 s17, s81, 0
	v_mov_b32_e32 v0, 0
	global_load_dword v0, v0, s[16:17] sc1
	s_waitcnt vmcnt(0)
	v_cmp_eq_u32_e32 vcc, 6, v0
	s_and_saveexec_b64 s[12:13], vcc
	s_cbranch_execz .LBB0_907
	s_add_u32 s14, s80, 0x1d80200
	s_addc_u32 s15, s81, 0
	s_mov_b32 s28, 1
	s_mov_b64 s[18:19], 0
	v_mov_b32_e32 v0, 0
	s_branch .LBB0_898

; DI unsigned xb_ld(unsigned* p)              { return __hip_atomic_load(p, __ATOMIC_RELAXED, __HIP_MEMORY_SCOPE_AGENT); }
; DI unsigned xb_add(unsigned* p, unsigned v) { return __hip_atomic_fetch_add(p, v, __ATOMIC_RELAXED, __HIP_MEMORY_SCOPE_AGENT); }
; #define XB_SPIN(cond, bar) do { unsigned _sp = 0; while (cond) { __builtin_amdgcn_s_sleep(1); \
;     if ((++_sp & 255u) == 0u) { if (xb_ld(&(bar)[XB_TMO])) break; if (_sp > XB_SPIN_CAP) { atomicAdd(&(bar)[XB_TMO], 1u); break; } } } } while (0)
; DI void xcd_barrier(const XcdBarrier& b, const int wid_s) {
;     ...
;             else XB_SPIN(xb_ld(&bar[XB_TOPGEN]) == tg, bar);
;             __builtin_amdgcn_fence(__ATOMIC_ACQUIRE, "agent");
;             xb_add(&bar[XB_XGEN(b.x)], 1u);
;             asm volatile("s_waitcnt vmcnt(0)" ::: "memory");
;         } else {
;             XB_SPIN(xb_ld(&bar[XB_XGEN(b.x)]) == gen, bar);
.LBB0_902:
	global_load_dword v2, v0, s[16:17] sc1
	s_add_i32 s28, s28, 1
	s_mov_b64 s[24:25], -1
	s_waitcnt vmcnt(0)
	v_cmp_ne_u32_e32 vcc, 6, v2
	s_orn2_b64 s[22:23], vcc, exec
	s_branch .LBB0_897

; DI unsigned xb_ld(unsigned* p)              { return __hip_atomic_load(p, __ATOMIC_RELAXED, __HIP_MEMORY_SCOPE_AGENT); }
; DI unsigned xb_add(unsigned* p, unsigned v) { return __hip_atomic_fetch_add(p, v, __ATOMIC_RELAXED, __HIP_MEMORY_SCOPE_AGENT); }
; #define XB_SPIN(cond, bar) do { unsigned _sp = 0; while (cond) { __builtin_amdgcn_s_sleep(1); \
;     if ((++_sp & 255u) == 0u) { if (xb_ld(&(bar)[XB_TMO])) break; if (_sp > XB_SPIN_CAP) { atomicAdd(&(bar)[XB_TMO], 1u); break; } } } } while (0)
; DI void xcd_barrier(const XcdBarrier& b, const int wid_s) {
;     ...
;             __builtin_amdgcn_fence(__ATOMIC_RELEASE, "agent");
;             asm volatile("s_waitcnt vmcnt(0)" ::: "memory");
;             const unsigned og = xb_add(&bar[XB_TOP], 1u);
;             const unsigned tg = og / nx;
;             if (og + 1u == (tg + 1u) * nx) xb_add(&bar[XB_TOPGEN], 1u);
;             else XB_SPIN(xb_ld(&bar[XB_TOPGEN]) == tg, bar);
;             __builtin_amdgcn_fence(__ATOMIC_ACQUIRE, "agent");
;             xb_add(&bar[XB_XGEN(b.x)], 1u);
;             asm volatile("s_waitcnt vmcnt(0)" ::: "memory");
.LBB0_925:
	s_or_b64 exec, exec, s[10:11]
	s_mov_b64 s[10:11], exec
	v_mbcnt_lo_u32_b32 v0, s10, 0
	v_mbcnt_hi_u32_b32 v0, s11, v0
	v_cmp_eq_u32_e32 vcc, 0, v0
	s_waitcnt vmcnt(0)
	buffer_inv sc1
	s_and_saveexec_b64 s[12:13], vcc
	s_cbranch_execz .LBB0_927
	s_bcnt1_i32_b64 s10, s[10:11]
.LBB0_927:
	s_or_b64 exec, exec, s[12:13]
	s_waitcnt vmcnt(0)
